# prompt attention QK: K-fragment LDS reads hoisted ahead of the 24 MFMAs
# speedup vs baseline: 1.0211x; 1.0049x over previous
; #define LAS __attribute__((address_space(3)))
; __device__ __forceinline__ float xor16_get(float v) { return __builtin_bit_cast(float, __builtin_amdgcn_ds_swizzle(__builtin_bit_cast(int, v), 0x401F)); }
; __device__ __forceinline__ float xor32_max(float v) { const unsigned u = __builtin_bit_cast(unsigned, v); auto r = __builtin_amdgcn_permlane32_swap(u, u, false, false); return fmaxf(__builtin_bit_cast(float, (unsigned)r[0]), __builtin_bit_cast(float, (unsigned)r[1])); }
; __device__ __forceinline__ f32x4 mfma16(bf16x8 a, bf16x8 b, f32x4 c) { return __builtin_amdgcn_mfma_f32_16x16x32_bf16(a, b, c, 0, 0, 0); }
; __device__ __forceinline__ void attn_prompt_unit(const PP P, LAS unsigned char* lds, int b, int h, int qt) {
;     ...
;             f32x4 s[2][4];
; #pragma unroll
;             for (int sb = 0; sb < 4; ++sb) { s[0][sb] = (f32x4){0.f, 0.f, 0.f, 0.f}; s[1][sb] = (f32x4){0.f, 0.f, 0.f, 0.f};
; #pragma unroll
;                 for (int ks = 0; ks < 3; ++ks) { const bf16x8 kf = *(const LAS bf16x8*)(kb + (16 * sb + fr) * AT_KROW + ks * 64 + fq * 16);
;                     s[0][sb] = mfma16(kf, Qb[0][ks], s[0][sb]); s[1][sb] = mfma16(kf, Qb[1][ks], s[1][sb]); } }
;             bf16x8 Pb[2][2];
; #pragma unroll
;             for (int g = 0; g < 2; ++g) {
;                 float mx = -INFINITY;
; #pragma unroll
;                 for (int sb = 0; sb < 4; ++sb) mx = fmaxf(mx, fmaxf(fmaxf(s[g][sb][0], s[g][sb][1]), fmaxf(s[g][sb][2], s[g][sb][3])));
;                 mx = fmaxf(mx, xor16_get(mx)); mx = xor32_max(mx);
;                 const float mnew = fmaxf(m[g], mx), alpha = __builtin_amdgcn_exp2f(m[g] - mnew); m[g] = mnew;
.LBB0_44:
	s_or_b64 exec, exec, s[2:3]
	v_cmp_le_i32_e32 vcc, s26, v121
	s_and_saveexec_b64 s[2:3], vcc
	s_cbranch_execz .LBB0_46
	s_bitcmp1_b32 s26, 0
	s_cselect_b32 s27, 0x5800, 0
	s_add_i32 s27, s27, 0
	v_add3_u32 v73, s27, v98, v147
	ds_read_b128 v[200:203], v73
	ds_read_b128 v[204:207], v73 offset:64
	ds_read_b128 v[208:211], v73 offset:128
	ds_read_b128 v[212:215], v73 offset:3328
	ds_read_b128 v[216:219], v73 offset:3392
	ds_read_b128 v[220:223], v73 offset:3456
	ds_read_b128 v[224:227], v73 offset:6656
	ds_read_b128 v[228:231], v73 offset:6720
	ds_read_b128 v[232:235], v73 offset:6784
	ds_read_b128 v[236:239], v73 offset:9984
	ds_read_b128 v[240:243], v73 offset:10048
	ds_read_b128 v[244:247], v73 offset:10112
	s_waitcnt lgkmcnt(11)
	v_mfma_f32_16x16x32_bf16 v[154:157], v[200:203], v[40:43], 0
	v_mfma_f32_16x16x32_bf16 v[80:83], v[200:203], v[28:31], 0
	s_waitcnt lgkmcnt(10)
	v_mfma_f32_16x16x32_bf16 v[154:157], v[204:207], v[36:39], v[154:157]
	v_mfma_f32_16x16x32_bf16 v[80:83], v[204:207], v[20:23], v[80:83]
	s_waitcnt lgkmcnt(9)
	v_mfma_f32_16x16x32_bf16 v[154:157], v[208:211], v[32:35], v[154:157]
	v_mfma_f32_16x16x32_bf16 v[80:83], v[208:211], v[16:19], v[80:83]
	s_waitcnt lgkmcnt(8)
	v_mfma_f32_16x16x32_bf16 v[158:161], v[212:215], v[40:43], 0
	v_mfma_f32_16x16x32_bf16 v[84:87], v[212:215], v[28:31], 0
	s_waitcnt lgkmcnt(7)
	v_mfma_f32_16x16x32_bf16 v[158:161], v[216:219], v[36:39], v[158:161]
	v_mfma_f32_16x16x32_bf16 v[84:87], v[216:219], v[20:23], v[84:87]
	s_waitcnt lgkmcnt(6)
	v_mfma_f32_16x16x32_bf16 v[158:161], v[220:223], v[32:35], v[158:161]
	v_mfma_f32_16x16x32_bf16 v[84:87], v[220:223], v[16:19], v[84:87]
	s_waitcnt lgkmcnt(5)
	v_mfma_f32_16x16x32_bf16 v[178:181], v[224:227], v[40:43], 0
	v_mfma_f32_16x16x32_bf16 v[88:91], v[224:227], v[28:31], 0
	s_waitcnt lgkmcnt(4)
	v_mfma_f32_16x16x32_bf16 v[178:181], v[228:231], v[36:39], v[178:181]
	v_mfma_f32_16x16x32_bf16 v[88:91], v[228:231], v[20:23], v[88:91]
	s_waitcnt lgkmcnt(3)
	v_mfma_f32_16x16x32_bf16 v[178:181], v[232:235], v[32:35], v[178:181]
	v_mfma_f32_16x16x32_bf16 v[88:91], v[232:235], v[16:19], v[88:91]
	s_waitcnt lgkmcnt(2)
	v_mfma_f32_16x16x32_bf16 v[182:185], v[236:239], v[40:43], 0
	v_mfma_f32_16x16x32_bf16 v[92:95], v[236:239], v[28:31], 0
	s_waitcnt lgkmcnt(1)
	v_mfma_f32_16x16x32_bf16 v[182:185], v[240:243], v[36:39], v[182:185]
	v_mfma_f32_16x16x32_bf16 v[92:95], v[240:243], v[20:23], v[92:95]
	s_waitcnt lgkmcnt(0)
	v_mfma_f32_16x16x32_bf16 v[182:185], v[244:247], v[32:35], v[182:185]
	v_mfma_f32_16x16x32_bf16 v[92:95], v[244:247], v[16:19], v[92:95]
	s_nop 7
	s_nop 1
	v_max_f32_e32 v125, v83, v83
	v_max_f32_e32 v73, v157, v157
	v_max_f32_e32 v139, v86, v86
	s_nop 1
	v_max_f32_e32 v74, v156, v156
	v_max_f32_e32 v73, v74, v73
	v_max_f32_e32 v74, v161, v161
	v_max_f32_e32 v75, v160, v160
	v_max_f32_e32 v74, v75, v74
	v_max3_f32 v73, v154, v155, v73
	v_max3_f32 v74, v158, v159, v74
	v_max3_f32 v73, v73, s37, v74
	v_max_f32_e32 v74, v181, v181
	v_max_f32_e32 v75, v180, v180
	v_max_f32_e32 v74, v75, v74
	v_max_f32_e32 v75, v185, v185
	v_max_f32_e32 v76, v184, v184
	v_max_f32_e32 v75, v76, v75
	v_max3_f32 v74, v178, v179, v74
	v_max3_f32 v75, v182, v183, v75
	v_max3_f32 v73, v73, v74, v75
	ds_swizzle_b32 v74, v73 offset:swizzle(SWAP,16)
	v_max_f32_e32 v141, v94, v94
	s_waitcnt lgkmcnt(0)
	v_max_f32_e32 v74, v74, v74
	v_max_f32_e32 v73, v73, v74
	v_mov_b32_e32 v74, v73
	s_nop 1
	v_permlane32_swap_b32_e32 v73, v74
	v_max3_f32 v123, v72, v73, v74
	v_sub_f32_e32 v72, v72, v123
	v_exp_f32_e32 v136, v72
	v_sub_f32_e32 v72, v154, v123
	v_exp_f32_e32 v138, v72
	v_sub_f32_e32 v72, v155, v123
	v_pk_mul_f32 v[46:47], v[46:47], v[136:137] op_sel_hi:[1,0]
	v_pk_mul_f32 v[44:45], v[44:45], v[136:137] op_sel_hi:[1,0]
	v_pk_mul_f32 v[54:55], v[54:55], v[136:137] op_sel_hi:[1,0]
	v_pk_mul_f32 v[52:53], v[52:53], v[136:137] op_sel_hi:[1,0]
	v_pk_mul_f32 v[58:59], v[58:59], v[136:137] op_sel_hi:[1,0]
	v_pk_mul_f32 v[56:57], v[56:57], v[136:137] op_sel_hi:[1,0]
	v_pk_mul_f32 v[70:71], v[70:71], v[136:137] op_sel_hi:[1,0]
	v_pk_mul_f32 v[68:69], v[68:69], v[136:137] op_sel_hi:[1,0]
	v_max_f32_e32 v137, v82, v82
	v_max_f32_e32 v125, v137, v125
	v_max_f32_e32 v137, v87, v87
	v_max_f32_e32 v137, v139, v137
	v_max3_f32 v125, v80, v81, v125
	v_max3_f32 v137, v84, v85, v137
	v_max3_f32 v125, v125, s37, v137
	v_max_f32_e32 v137, v91, v91
	v_max_f32_e32 v139, v90, v90
	v_max_f32_e32 v137, v139, v137
	v_max_f32_e32 v139, v95, v95
	v_max_f32_e32 v139, v141, v139
	v_max3_f32 v137, v88, v89, v137
	v_max3_f32 v139, v92, v93, v139
	v_max3_f32 v125, v125, v137, v139
	ds_swizzle_b32 v137, v125 offset:swizzle(SWAP,16)
	v_exp_f32_e32 v140, v72
	v_sub_f32_e32 v72, v156, v123
	v_exp_f32_e32 v154, v72
	v_sub_f32_e32 v72, v157, v123
	s_waitcnt lgkmcnt(0)
; #define LAS __attribute__((address_space(3)))
; __device__ __forceinline__ unsigned pk2(float lo, float hi) { const f32x2_ v = {lo, hi}; return __builtin_bit_cast(unsigned, __builtin_convertvector(v, bf16x2_)); }
; __device__ __forceinline__ f32x4 mfma16(bf16x8 a, bf16x8 b, f32x4 c) { return __builtin_amdgcn_mfma_f32_16x16x32_bf16(a, b, c, 0, 0, 0); }
; __device__ __forceinline__ void attn_prompt_unit(const PP P, LAS unsigned char* lds, int b, int h, int qt) {
;     ...
;                 const float mnew = fmaxf(m[g], mx), alpha = __builtin_amdgcn_exp2f(m[g] - mnew); m[g] = mnew;
;                 float ps = 0.f; float p[4][4];
; #pragma unroll
;                 for (int sb = 0; sb < 4; ++sb)
; #pragma unroll
;                     for (int j = 0; j < 4; ++j) { p[sb][j] = __builtin_amdgcn_exp2f(s[g][sb][j] - mnew); ps += p[sb][j]; }
;                 lsum[g] = lsum[g] * alpha + ps;
; #pragma unroll
;                 for (int kk = 0; kk < 2; ++kk) { u32x4 pw; pw.x = pk2(p[2 * kk][0], p[2 * kk][1]); pw.y = pk2(p[2 * kk][2], p[2 * kk][3]); pw.z = pk2(p[2 * kk + 1][0], p[2 * kk + 1][1]); pw.w = pk2(p[2 * kk + 1][2], p[2 * kk + 1][3]);
;                     Pb[g][kk] = __builtin_bit_cast(bf16x8, pw); }
; #pragma unroll
;                 for (int nt = 0; nt < 4; ++nt) O[g][nt] = O[g][nt] * alpha;
;             }
; #pragma unroll
;             for (int nt = 0; nt < 4; ++nt)
; #pragma unroll
;                 for (int kk = 0; kk < 2; ++kk) { const LAS unsigned char* vp = vb + (16 * nt + fr) * AT_VROW + kk * 64 + fq * 8;
;                     const s16x4 a = *(const LAS s16x4*)vp, c = *(const LAS s16x4*)(vp + 32);
;                     bf16x8 vf; vf[0] = a[0]; vf[1] = a[1]; vf[2] = a[2]; vf[3] = a[3]; vf[4] = c[0]; vf[5] = c[1]; vf[6] = c[2]; vf[7] = c[3];
;                     O[0][nt] = mfma16(vf, Pb[0][kk], O[0][nt]); O[1][nt] = mfma16(vf, Pb[1][kk], O[1][nt]); }
	v_max_f32_e32 v137, v137, v137
	v_max_f32_e32 v125, v125, v137
	v_mov_b32_e32 v137, v125
	s_nop 1
	v_permlane32_swap_b32_e32 v125, v137
	v_max3_f32 v125, v24, v125, v137
	v_sub_f32_e32 v24, v24, v125
	v_exp_f32_e32 v137, v24
	v_sub_f32_e32 v24, v80, v125
	v_exp_f32_e32 v139, v24
	v_sub_f32_e32 v24, v81, v125
	v_exp_f32_e32 v141, v24
	v_sub_f32_e32 v24, v82, v125
	v_exp_f32_e32 v155, v24
	v_sub_f32_e32 v24, v83, v125
	v_exp_f32_e32 v156, v72
	v_sub_f32_e32 v72, v158, v123
	v_exp_f32_e32 v157, v24
	v_sub_f32_e32 v24, v84, v125
	v_exp_f32_e32 v158, v72
	v_sub_f32_e32 v72, v159, v123
	v_exp_f32_e32 v159, v24
	v_sub_f32_e32 v24, v85, v125
	v_exp_f32_e32 v162, v72
	v_sub_f32_e32 v72, v160, v123
	v_exp_f32_e32 v163, v24
	v_sub_f32_e32 v24, v86, v125
	v_exp_f32_e32 v160, v72
	v_sub_f32_e32 v72, v161, v123
	v_exp_f32_e32 v161, v24
	v_sub_f32_e32 v24, v87, v125
	v_exp_f32_e32 v186, v72
	v_sub_f32_e32 v72, v178, v123
	v_exp_f32_e32 v187, v24
	v_sub_f32_e32 v24, v88, v125
	v_exp_f32_e32 v178, v72
	v_sub_f32_e32 v72, v179, v123
	v_exp_f32_e32 v179, v24
	v_sub_f32_e32 v24, v89, v125
	v_exp_f32_e32 v188, v72
	v_sub_f32_e32 v72, v180, v123
	v_exp_f32_e32 v189, v24
	v_sub_f32_e32 v24, v90, v125
	v_exp_f32_e32 v180, v72
	v_sub_f32_e32 v72, v181, v123
	v_exp_f32_e32 v181, v24
	v_sub_f32_e32 v24, v91, v125
	v_exp_f32_e32 v190, v72
	v_sub_f32_e32 v72, v182, v123
	v_exp_f32_e32 v191, v24
	v_sub_f32_e32 v24, v92, v125
	v_exp_f32_e32 v182, v72
	v_sub_f32_e32 v72, v183, v123
	v_exp_f32_e32 v183, v24
	v_sub_f32_e32 v24, v93, v125
	v_exp_f32_e32 v192, v72
	v_sub_f32_e32 v72, v184, v123
	v_exp_f32_e32 v193, v24
	v_sub_f32_e32 v24, v94, v125
	v_exp_f32_e32 v184, v72
	v_sub_f32_e32 v72, v185, v123
	v_exp_f32_e32 v185, v24
	v_sub_f32_e32 v24, v95, v125
	v_exp_f32_e32 v195, v24
	v_mov_b32_e32 v24, v137
	v_pk_mul_f32 v[6:7], v[6:7], v[24:25] op_sel_hi:[1,0]
	v_pk_mul_f32 v[4:5], v[4:5], v[24:25] op_sel_hi:[1,0]
	v_pk_mul_f32 v[2:3], v[2:3], v[24:25] op_sel_hi:[1,0]
	v_pk_mul_f32 v[0:1], v[0:1], v[24:25] op_sel_hi:[1,0]
	v_pk_mul_f32 v[10:11], v[10:11], v[24:25] op_sel_hi:[1,0]
	v_pk_mul_f32 v[8:9], v[8:9], v[24:25] op_sel_hi:[1,0]
	v_pk_mul_f32 v[14:15], v[14:15], v[24:25] op_sel_hi:[1,0]
	v_pk_mul_f32 v[12:13], v[12:13], v[24:25] op_sel_hi:[1,0]
	v_add3_u32 v24, s27, v96, v148
	v_add_u32_e32 v92, 0x3000, v24
	ds_read2_b64 v[88:91], v92 offset0:128 offset1:132
	v_pk_add_f32 v[80:81], v[138:139], 0 op_sel_hi:[1,0]
	v_cvt_pk_bf16_f32 v76, v138, v140
	v_pk_add_f32 v[80:81], v[140:141], v[80:81]
	v_cvt_pk_bf16_f32 v77, v154, v156
	v_pk_add_f32 v[80:81], v[154:155], v[80:81]
	v_cvt_pk_bf16_f32 v78, v158, v162
	v_pk_add_f32 v[80:81], v[156:157], v[80:81]
	v_cvt_pk_bf16_f32 v79, v160, v186
	v_pk_add_f32 v[80:81], v[158:159], v[80:81]
	v_cvt_pk_bf16_f32 v84, v139, v141
	v_pk_add_f32 v[80:81], v[162:163], v[80:81]
	v_cvt_pk_bf16_f32 v85, v155, v157
	v_pk_add_f32 v[80:81], v[160:161], v[80:81]
	v_cvt_pk_bf16_f32 v86, v159, v163
	v_pk_add_f32 v[80:81], v[186:187], v[80:81]
	v_cvt_pk_bf16_f32 v87, v161, v187
	v_pk_add_f32 v[80:81], v[178:179], v[80:81]
	s_waitcnt lgkmcnt(0)
	v_mfma_f32_16x16x32_bf16 v[44:47], v[88:91], v[76:79], v[44:47]
	v_add_f32_e64 v80, v188, v80
	v_add_f32_e64 v81, v189, v81
	v_exp_f32_e32 v194, v72
	v_pk_add_f32 v[80:81], v[180:181], v[80:81]
	v_mfma_f32_16x16x32_bf16 v[4:7], v[88:91], v[84:87], v[4:7]
	ds_read2_b64 v[88:91], v92 offset0:136 offset1:140
	v_pk_add_f32 v[80:81], v[190:191], v[80:81]
	v_cvt_pk_bf16_f32 v72, v178, v188
	v_pk_add_f32 v[80:81], v[182:183], v[80:81]
	v_cvt_pk_bf16_f32 v73, v180, v190
	v_pk_add_f32 v[80:81], v[192:193], v[80:81]
	v_cvt_pk_bf16_f32 v74, v182, v192
	v_pk_add_f32 v[80:81], v[184:185], v[80:81]
	v_cvt_pk_bf16_f32 v75, v184, v194
	v_pk_add_f32 v[80:81], v[194:195], v[80:81]
	v_cvt_pk_bf16_f32 v82, v183, v193
	v_pk_fma_f32 v[130:131], v[130:131], v[136:137], v[80:81]
	v_cvt_pk_bf16_f32 v80, v179, v189
	v_cvt_pk_bf16_f32 v81, v181, v191
	v_cvt_pk_bf16_f32 v83, v185, v195
	v_add_u32_e32 v92, 0x3800, v24
	s_waitcnt lgkmcnt(0)
	v_mfma_f32_16x16x32_bf16 v[44:47], v[88:91], v[72:75], v[44:47]
	v_mfma_f32_16x16x32_bf16 v[4:7], v[88:91], v[80:83], v[4:7]
	ds_read2_b64 v[88:91], v92 offset0:160 offset1:164
	s_waitcnt lgkmcnt(0)
	v_mfma_f32_16x16x32_bf16 v[52:55], v[88:91], v[76:79], v[52:55]
	v_mfma_f32_16x16x32_bf16 v[0:3], v[88:91], v[84:87], v[0:3]
	ds_read2_b64 v[88:91], v92 offset0:168 offset1:172
	v_add_u32_e32 v92, 0x4000, v24
	v_add_u32_e32 v24, 0x4800, v24
	s_waitcnt lgkmcnt(0)
	v_mfma_f32_16x16x32_bf16 v[52:55], v[88:91], v[72:75], v[52:55]
	v_mfma_f32_16x16x32_bf16 v[0:3], v[88:91], v[80:83], v[0:3]
	ds_read2_b64 v[88:91], v92 offset0:192 offset1:196
	s_waitcnt lgkmcnt(0)
	v_mfma_f32_16x16x32_bf16 v[56:59], v[88:91], v[76:79], v[56:59]
	v_mfma_f32_16x16x32_bf16 v[8:11], v[88:91], v[84:87], v[8:11]
	ds_read2_b64 v[88:91], v92 offset0:200 offset1:204
	s_waitcnt lgkmcnt(0)
	v_mfma_f32_16x16x32_bf16 v[56:59], v[88:91], v[72:75], v[56:59]
	v_mfma_f32_16x16x32_bf16 v[8:11], v[88:91], v[80:83], v[8:11]
	ds_read2_b64 v[88:91], v24 offset0:224 offset1:228
	s_waitcnt lgkmcnt(0)
	v_mfma_f32_16x16x32_bf16 v[68:71], v[88:91], v[76:79], v[68:71]
	ds_read2_b64 v[76:79], v24 offset0:232 offset1:236
	v_mov_b32_e32 v24, v125
	v_mfma_f32_16x16x32_bf16 v[12:15], v[88:91], v[84:87], v[12:15]
	s_waitcnt lgkmcnt(0)
	v_mfma_f32_16x16x32_bf16 v[68:71], v[76:79], v[72:75], v[68:71]
	v_mov_b32_e32 v72, v123
	v_mfma_f32_16x16x32_bf16 v[12:15], v[76:79], v[80:83], v[12:15]
